# consecutive dil items per CU, padded so all later code sits exactly +256 bytes from best2 offsets
# baseline (speedup 1.0000x reference)
; __global__ void __launch_bounds__(512, 2) fwd_megakernel(Params p) {
;     ...
;     for (int it = bid; it < 128 + 384; it += G) {
.LBB0_264:
	v_readlane_b32 s0, v253, 12
	s_nop 1
	s_cmpk_lg_u32 s0, 0x100
	s_cbranch_scc1 .Lp2a_generic
	s_cmpk_lt_i32 s13, 0x80
	s_cbranch_scc1 .LBB0_332
	s_add_i32 s13, s13, 1
	s_sub_i32 s0, s13, 0x80
	s_mul_i32 s1, s0, 0xaaab
	s_lshr_b32 s1, s1, 17
	s_mul_i32 s1, s1, 3
	s_cmp_eq_u32 s1, s0
	s_cbranch_scc1 .LBB0_332
	s_branch .LBB0_265
	s_nop 0
	s_nop 0
	s_nop 0
	s_nop 0
	s_nop 0
	s_nop 0
	s_nop 0
	s_nop 0
	s_nop 0
	s_nop 0
	s_nop 0
	s_nop 0
	s_nop 0
	s_nop 0
	s_nop 0
	s_nop 0
	s_nop 0
	s_nop 0
	s_nop 0
	s_nop 0
	s_nop 0
	s_nop 0
	s_nop 0
	s_nop 0
	s_nop 0
	s_nop 0
	s_nop 0
	s_nop 0
	s_nop 0
	s_nop 0
	s_nop 0
	s_nop 0
	s_nop 0
	s_nop 0
	s_nop 0
	s_nop 0
	s_nop 0
	s_nop 0
	s_nop 0
	s_nop 0
	s_nop 0
	s_nop 0
	s_nop 0
	s_nop 0
	s_nop 0
	s_nop 0
